# down-proj epilogue rewritten (row-folded prefetched residual add); K-split sample tail atomics re-laid out through per-wave LDS scratch so each f32 atomic covers full 64-B segments
# speedup vs baseline: 1.3964x; 1.0360x over previous
.LBB0_1640:
	ds_read_b128 v[146:149], v155
	ds_read_b128 v[160:163], v155 offset:1024
	ds_read_b128 v[164:167], v155 offset:2048
	ds_read_b128 v[168:171], v155 offset:3072
	s_add_i32 s73, s44, 2
	s_add_u32 s74, s38, 0xffea0080
	s_addc_u32 s45, s39, -1
	s_cmp_eq_u32 s70, s44
	s_cselect_b32 s44, s6, s74
	s_cselect_b32 s45, s7, s45
	s_cselect_b32 s75, s9, s72
	s_cselect_b32 s74, s8, s71
	v_lshl_add_u64 v[150:151], s[38:39], 0, v[136:137]
	s_add_i32 m0, s52, 0xc000
	ds_read_b128 v[172:175], v157
	ds_read_b128 v[176:179], v157 offset:1024
	ds_read_b128 v[180:183], v157 offset:2048
	ds_read_b128 v[184:187], v157 offset:3072
	ds_read_b128 v[188:191], v157 offset:4096
	ds_read_b128 v[192:195], v157 offset:5120
	ds_read_b128 v[196:199], v157 offset:6144
	ds_read_b128 v[200:203], v157 offset:7168
	global_load_lds_dwordx4 v[150:151], off
	v_lshl_add_u64 v[150:151], s[38:39], 0, v[138:139]
	s_add_i32 m0, s52, 0xe000
	s_nop 0
	global_load_lds_dwordx4 v[150:151], off
	s_waitcnt lgkmcnt(8)
	s_barrier
	s_waitcnt lgkmcnt(0)
	s_setprio 1
	s_waitcnt lgkmcnt(0)
	v_mfma_f32_16x16x32_bf16 v[124:127], v[146:149], v[172:175], v[124:127]
	v_mfma_f32_16x16x32_bf16 v[120:123], v[164:167], v[172:175], v[120:123]
	v_mfma_f32_16x16x32_bf16 v[108:111], v[146:149], v[180:183], v[108:111]
	v_mfma_f32_16x16x32_bf16 v[104:107], v[164:167], v[180:183], v[104:107]
	v_mfma_f32_16x16x32_bf16 v[92:95], v[146:149], v[188:191], v[92:95]
	v_mfma_f32_16x16x32_bf16 v[88:91], v[164:167], v[188:191], v[88:91]
	v_mfma_f32_16x16x32_bf16 v[76:79], v[146:149], v[196:199], v[76:79]
	v_mfma_f32_16x16x32_bf16 v[72:75], v[164:167], v[196:199], v[72:75]
	v_mfma_f32_16x16x32_bf16 v[124:127], v[160:163], v[176:179], v[124:127]
	v_mfma_f32_16x16x32_bf16 v[120:123], v[168:171], v[176:179], v[120:123]
	v_mfma_f32_16x16x32_bf16 v[108:111], v[160:163], v[184:187], v[108:111]
	v_mfma_f32_16x16x32_bf16 v[104:107], v[168:171], v[184:187], v[104:107]
	v_mfma_f32_16x16x32_bf16 v[92:95], v[160:163], v[192:195], v[92:95]
	v_mfma_f32_16x16x32_bf16 v[88:91], v[168:171], v[192:195], v[88:91]
	v_mfma_f32_16x16x32_bf16 v[76:79], v[160:163], v[200:203], v[76:79]
	v_mfma_f32_16x16x32_bf16 v[72:75], v[168:171], v[200:203], v[72:75]
	s_setprio 0
	s_barrier
	v_lshl_add_u64 v[150:151], s[74:75], 0, v[128:129]
	s_add_i32 s74, s63, s51
	s_mov_b32 m0, s74
	ds_read_b128 v[204:207], v158
	ds_read_b128 v[208:211], v158 offset:1024
	ds_read_b128 v[212:215], v158 offset:2048
	ds_read_b128 v[216:219], v158 offset:3072
	global_load_lds_dwordx4 v[150:151], off
	v_lshl_add_u64 v[220:221], v[150:151], 0, s[26:27]
	s_add_i32 m0, s74, 0x2000
	s_nop 0
	global_load_lds_dwordx4 v[220:221], off
	s_barrier
	s_waitcnt lgkmcnt(0)
	s_setprio 1
	s_waitcnt lgkmcnt(0)
	v_mfma_f32_16x16x32_bf16 v[116:119], v[204:207], v[172:175], v[116:119]
	v_mfma_f32_16x16x32_bf16 v[112:115], v[212:215], v[172:175], v[112:115]
	v_mfma_f32_16x16x32_bf16 v[100:103], v[204:207], v[180:183], v[100:103]
	v_mfma_f32_16x16x32_bf16 v[96:99], v[212:215], v[180:183], v[96:99]
	v_mfma_f32_16x16x32_bf16 v[84:87], v[204:207], v[188:191], v[84:87]
	v_mfma_f32_16x16x32_bf16 v[80:83], v[212:215], v[188:191], v[80:83]
	v_mfma_f32_16x16x32_bf16 v[68:71], v[204:207], v[196:199], v[68:71]
	v_mfma_f32_16x16x32_bf16 v[64:67], v[212:215], v[196:199], v[64:67]
	v_mfma_f32_16x16x32_bf16 v[116:119], v[208:211], v[176:179], v[116:119]
	v_mfma_f32_16x16x32_bf16 v[112:115], v[216:219], v[176:179], v[112:115]
	v_mfma_f32_16x16x32_bf16 v[100:103], v[208:211], v[184:187], v[100:103]
	v_mfma_f32_16x16x32_bf16 v[96:99], v[216:219], v[184:187], v[96:99]
	v_mfma_f32_16x16x32_bf16 v[84:87], v[208:211], v[192:195], v[84:87]
	v_mfma_f32_16x16x32_bf16 v[80:83], v[216:219], v[192:195], v[80:83]
	v_mfma_f32_16x16x32_bf16 v[68:71], v[208:211], v[200:203], v[68:71]
	v_mfma_f32_16x16x32_bf16 v[64:67], v[216:219], v[200:203], v[64:67]
	s_setprio 0
	s_mov_b32 m0, s52
	v_lshl_add_u64 v[220:221], s[44:45], 0, v[130:131]
	s_barrier
	ds_read_b128 v[172:175], v157 offset:16384
	ds_read_b128 v[176:179], v157 offset:17408
	ds_read_b128 v[180:183], v157 offset:18432
	ds_read_b128 v[184:187], v157 offset:19456
	ds_read_b128 v[188:191], v157 offset:20480
	ds_read_b128 v[192:195], v157 offset:21504
	ds_read_b128 v[196:199], v157 offset:22528
	ds_read_b128 v[200:203], v157 offset:23552
	global_load_lds_dwordx4 v[220:221], off
	v_lshl_add_u64 v[222:223], s[44:45], 0, v[134:135]
	s_mov_b32 m0, s53
	s_nop 0
	global_load_lds_dwordx4 v[222:223], off
	s_barrier
	s_waitcnt lgkmcnt(0)
	s_setprio 1
	s_waitcnt lgkmcnt(0)
	v_mfma_f32_16x16x32_bf16 v[60:63], v[146:149], v[172:175], v[60:63]
	v_mfma_f32_16x16x32_bf16 v[56:59], v[164:167], v[172:175], v[56:59]
	v_mfma_f32_16x16x32_bf16 v[44:47], v[146:149], v[180:183], v[44:47]
	v_mfma_f32_16x16x32_bf16 v[40:43], v[164:167], v[180:183], v[40:43]
	v_mfma_f32_16x16x32_bf16 v[28:31], v[146:149], v[188:191], v[28:31]
	v_mfma_f32_16x16x32_bf16 v[24:27], v[164:167], v[188:191], v[24:27]
	v_mfma_f32_16x16x32_bf16 v[12:15], v[146:149], v[196:199], v[12:15]
	v_mfma_f32_16x16x32_bf16 v[8:11], v[164:167], v[196:199], v[8:11]
	v_mfma_f32_16x16x32_bf16 v[60:63], v[160:163], v[176:179], v[60:63]
	v_mfma_f32_16x16x32_bf16 v[56:59], v[168:171], v[176:179], v[56:59]
	v_mfma_f32_16x16x32_bf16 v[44:47], v[160:163], v[184:187], v[44:47]
	v_mfma_f32_16x16x32_bf16 v[40:43], v[168:171], v[184:187], v[40:43]
	v_mfma_f32_16x16x32_bf16 v[28:31], v[160:163], v[192:195], v[28:31]
	v_mfma_f32_16x16x32_bf16 v[24:27], v[168:171], v[192:195], v[24:27]
	v_mfma_f32_16x16x32_bf16 v[12:15], v[160:163], v[200:203], v[12:15]
	v_mfma_f32_16x16x32_bf16 v[8:11], v[168:171], v[200:203], v[8:11]
	s_setprio 0
	s_barrier
	s_add_i32 s74, s64, s51
	v_lshl_add_u64 v[146:147], v[150:151], 0, s[14:15]
	s_mov_b32 m0, s74
	s_nop 0
	global_load_lds_dwordx4 v[146:147], off
	v_lshl_add_u64 v[146:147], v[150:151], 0, s[28:29]
	s_add_i32 m0, s74, 0x2000
	s_nop 0
	global_load_lds_dwordx4 v[146:147], off
	s_waitcnt vmcnt(6)
	s_barrier
	s_setprio 1
	v_mfma_f32_16x16x32_bf16 v[52:55], v[204:207], v[172:175], v[52:55]
	v_mfma_f32_16x16x32_bf16 v[48:51], v[212:215], v[172:175], v[48:51]
	v_mfma_f32_16x16x32_bf16 v[36:39], v[204:207], v[180:183], v[36:39]
	v_mfma_f32_16x16x32_bf16 v[32:35], v[212:215], v[180:183], v[32:35]
	v_mfma_f32_16x16x32_bf16 v[20:23], v[204:207], v[188:191], v[20:23]
	v_mfma_f32_16x16x32_bf16 v[16:19], v[212:215], v[188:191], v[16:19]
	v_mfma_f32_16x16x32_bf16 v[4:7], v[204:207], v[196:199], v[4:7]
	v_mfma_f32_16x16x32_bf16 v[0:3], v[212:215], v[196:199], v[0:3]
	v_mfma_f32_16x16x32_bf16 v[52:55], v[208:211], v[176:179], v[52:55]
	v_mfma_f32_16x16x32_bf16 v[48:51], v[216:219], v[176:179], v[48:51]
	v_mfma_f32_16x16x32_bf16 v[36:39], v[208:211], v[184:187], v[36:39]
	v_mfma_f32_16x16x32_bf16 v[32:35], v[216:219], v[184:187], v[32:35]
	v_mfma_f32_16x16x32_bf16 v[20:23], v[208:211], v[192:195], v[20:23]
	v_mfma_f32_16x16x32_bf16 v[16:19], v[216:219], v[192:195], v[16:19]
	v_mfma_f32_16x16x32_bf16 v[4:7], v[208:211], v[200:203], v[4:7]
	v_mfma_f32_16x16x32_bf16 v[0:3], v[216:219], v[200:203], v[0:3]
	s_setprio 0
	s_add_i32 s74, 0, 0x18000
	v_add_u32_e32 v132, s74, v153
	s_barrier
	ds_read_b128 v[146:149], v132
	ds_read_b128 v[160:163], v132 offset:1024
	ds_read_b128 v[164:167], v132 offset:2048
	ds_read_b128 v[168:171], v132 offset:3072
	s_add_u32 s44, s44, 0x160000
	s_addc_u32 s45, s45, 0
	s_mov_b32 m0, s54
	v_lshl_add_u64 v[204:205], s[44:45], 0, v[130:131]
	ds_read_b128 v[172:175], v157 offset:32768
	ds_read_b128 v[176:179], v157 offset:33792
	ds_read_b128 v[180:183], v157 offset:34816
	ds_read_b128 v[184:187], v157 offset:35840
	ds_read_b128 v[188:191], v157 offset:36864
	ds_read_b128 v[192:195], v157 offset:37888
	ds_read_b128 v[196:199], v157 offset:38912
	ds_read_b128 v[200:203], v157 offset:39936
	global_load_lds_dwordx4 v[204:205], off
	v_lshl_add_u64 v[204:205], s[44:45], 0, v[134:135]
	s_mov_b32 m0, s55
	s_nop 0
	global_load_lds_dwordx4 v[204:205], off
	s_waitcnt lgkmcnt(8)
	s_barrier
	s_waitcnt lgkmcnt(0)
	s_setprio 1
	s_waitcnt lgkmcnt(0)
	v_mfma_f32_16x16x32_bf16 v[124:127], v[146:149], v[172:175], v[124:127]
	v_mfma_f32_16x16x32_bf16 v[120:123], v[164:167], v[172:175], v[120:123]
	v_mfma_f32_16x16x32_bf16 v[108:111], v[146:149], v[180:183], v[108:111]
	v_mfma_f32_16x16x32_bf16 v[104:107], v[164:167], v[180:183], v[104:107]
	v_mfma_f32_16x16x32_bf16 v[92:95], v[146:149], v[188:191], v[92:95]
	v_mfma_f32_16x16x32_bf16 v[88:91], v[164:167], v[188:191], v[88:91]
	v_mfma_f32_16x16x32_bf16 v[76:79], v[146:149], v[196:199], v[76:79]
	v_mfma_f32_16x16x32_bf16 v[72:75], v[164:167], v[196:199], v[72:75]
	v_mfma_f32_16x16x32_bf16 v[124:127], v[160:163], v[176:179], v[124:127]
	v_mfma_f32_16x16x32_bf16 v[120:123], v[168:171], v[176:179], v[120:123]
	v_mfma_f32_16x16x32_bf16 v[108:111], v[160:163], v[184:187], v[108:111]
	v_mfma_f32_16x16x32_bf16 v[104:107], v[168:171], v[184:187], v[104:107]
	v_mfma_f32_16x16x32_bf16 v[92:95], v[160:163], v[192:195], v[92:95]
	v_mfma_f32_16x16x32_bf16 v[88:91], v[168:171], v[192:195], v[88:91]
	v_mfma_f32_16x16x32_bf16 v[76:79], v[160:163], v[200:203], v[76:79]
	v_mfma_f32_16x16x32_bf16 v[72:75], v[168:171], v[200:203], v[72:75]
	s_setprio 0
	s_barrier
	s_add_i32 s44, 0, 0x1c000
	s_add_i32 s45, s74, s51
	v_add_u32_e32 v132, s44, v153
	v_lshl_add_u64 v[224:225], v[150:151], 0, s[20:21]
	s_mov_b32 m0, s45
	ds_read_b128 v[204:207], v132
	ds_read_b128 v[208:211], v132 offset:1024
	ds_read_b128 v[212:215], v132 offset:2048
	ds_read_b128 v[216:219], v132 offset:3072
	global_load_lds_dwordx4 v[224:225], off
	v_lshl_add_u64 v[224:225], v[150:151], 0, s[30:31]
	s_add_i32 m0, s45, 0x2000
	s_nop 0
	global_load_lds_dwordx4 v[224:225], off
	s_barrier
	s_waitcnt lgkmcnt(0)
	s_setprio 1
	s_waitcnt lgkmcnt(0)
	v_mfma_f32_16x16x32_bf16 v[116:119], v[204:207], v[172:175], v[116:119]
	v_mfma_f32_16x16x32_bf16 v[112:115], v[212:215], v[172:175], v[112:115]
	v_mfma_f32_16x16x32_bf16 v[100:103], v[204:207], v[180:183], v[100:103]
	v_mfma_f32_16x16x32_bf16 v[96:99], v[212:215], v[180:183], v[96:99]
	v_mfma_f32_16x16x32_bf16 v[84:87], v[204:207], v[188:191], v[84:87]
	v_mfma_f32_16x16x32_bf16 v[80:83], v[212:215], v[188:191], v[80:83]
	v_mfma_f32_16x16x32_bf16 v[68:71], v[204:207], v[196:199], v[68:71]
	v_mfma_f32_16x16x32_bf16 v[64:67], v[212:215], v[196:199], v[64:67]
	v_mfma_f32_16x16x32_bf16 v[116:119], v[208:211], v[176:179], v[116:119]
	v_mfma_f32_16x16x32_bf16 v[112:115], v[216:219], v[176:179], v[112:115]
	v_mfma_f32_16x16x32_bf16 v[100:103], v[208:211], v[184:187], v[100:103]
	v_mfma_f32_16x16x32_bf16 v[96:99], v[216:219], v[184:187], v[96:99]
	v_mfma_f32_16x16x32_bf16 v[84:87], v[208:211], v[192:195], v[84:87]
	v_mfma_f32_16x16x32_bf16 v[80:83], v[216:219], v[192:195], v[80:83]
	v_mfma_f32_16x16x32_bf16 v[68:71], v[208:211], v[200:203], v[68:71]
	v_mfma_f32_16x16x32_bf16 v[64:67], v[216:219], v[200:203], v[64:67]
	s_setprio 0
	s_mov_b32 m0, s59
	v_lshl_add_u64 v[220:221], v[220:221], 0, s[18:19]
	s_barrier
	ds_read_b128 v[172:175], v157 offset:49152
	ds_read_b128 v[176:179], v157 offset:50176
	ds_read_b128 v[180:183], v157 offset:51200
	ds_read_b128 v[184:187], v157 offset:52224
	ds_read_b128 v[188:191], v157 offset:53248
	ds_read_b128 v[192:195], v157 offset:54272
	ds_read_b128 v[196:199], v157 offset:55296
	ds_read_b128 v[200:203], v157 offset:56320
	global_load_lds_dwordx4 v[220:221], off
	v_lshl_add_u64 v[220:221], v[222:223], 0, s[18:19]
	s_mov_b32 m0, s60
	s_nop 0
	global_load_lds_dwordx4 v[220:221], off
	s_barrier
	s_waitcnt lgkmcnt(0)
	s_setprio 1
	s_waitcnt lgkmcnt(0)
	v_mfma_f32_16x16x32_bf16 v[60:63], v[146:149], v[172:175], v[60:63]
	v_mfma_f32_16x16x32_bf16 v[56:59], v[164:167], v[172:175], v[56:59]
	v_mfma_f32_16x16x32_bf16 v[44:47], v[146:149], v[180:183], v[44:47]
	v_mfma_f32_16x16x32_bf16 v[40:43], v[164:167], v[180:183], v[40:43]
	v_mfma_f32_16x16x32_bf16 v[28:31], v[146:149], v[188:191], v[28:31]
	v_mfma_f32_16x16x32_bf16 v[24:27], v[164:167], v[188:191], v[24:27]
	v_mfma_f32_16x16x32_bf16 v[12:15], v[146:149], v[196:199], v[12:15]
	v_mfma_f32_16x16x32_bf16 v[8:11], v[164:167], v[196:199], v[8:11]
	v_mfma_f32_16x16x32_bf16 v[60:63], v[160:163], v[176:179], v[60:63]
	v_mfma_f32_16x16x32_bf16 v[56:59], v[168:171], v[176:179], v[56:59]
	v_mfma_f32_16x16x32_bf16 v[44:47], v[160:163], v[184:187], v[44:47]
	v_mfma_f32_16x16x32_bf16 v[40:43], v[168:171], v[184:187], v[40:43]
	v_mfma_f32_16x16x32_bf16 v[28:31], v[160:163], v[192:195], v[28:31]
	v_mfma_f32_16x16x32_bf16 v[24:27], v[168:171], v[192:195], v[24:27]
	v_mfma_f32_16x16x32_bf16 v[12:15], v[160:163], v[200:203], v[12:15]
	v_mfma_f32_16x16x32_bf16 v[8:11], v[168:171], v[200:203], v[8:11]
	s_setprio 0
	s_barrier
	s_add_i32 s44, s44, s51
	v_lshl_add_u64 v[146:147], v[150:151], 0, s[22:23]
	s_mov_b32 m0, s44
	s_nop 0
	global_load_lds_dwordx4 v[146:147], off
	v_lshl_add_u64 v[146:147], v[150:151], 0, s[34:35]
	s_add_i32 m0, s44, 0x2000
	s_nop 0
	global_load_lds_dwordx4 v[146:147], off
	s_waitcnt vmcnt(6)
	s_barrier
	s_setprio 1
	v_mfma_f32_16x16x32_bf16 v[52:55], v[204:207], v[172:175], v[52:55]
	v_mfma_f32_16x16x32_bf16 v[48:51], v[212:215], v[172:175], v[48:51]
	v_mfma_f32_16x16x32_bf16 v[36:39], v[204:207], v[180:183], v[36:39]
	v_mfma_f32_16x16x32_bf16 v[32:35], v[212:215], v[180:183], v[32:35]
	v_mfma_f32_16x16x32_bf16 v[20:23], v[204:207], v[188:191], v[20:23]
	v_mfma_f32_16x16x32_bf16 v[16:19], v[212:215], v[188:191], v[16:19]
	v_mfma_f32_16x16x32_bf16 v[4:7], v[204:207], v[196:199], v[4:7]
	v_mfma_f32_16x16x32_bf16 v[0:3], v[212:215], v[196:199], v[0:3]
	v_mfma_f32_16x16x32_bf16 v[52:55], v[208:211], v[176:179], v[52:55]
	v_mfma_f32_16x16x32_bf16 v[48:51], v[216:219], v[176:179], v[48:51]
	v_mfma_f32_16x16x32_bf16 v[36:39], v[208:211], v[184:187], v[36:39]
	v_mfma_f32_16x16x32_bf16 v[32:35], v[216:219], v[184:187], v[32:35]
	v_mfma_f32_16x16x32_bf16 v[20:23], v[208:211], v[192:195], v[20:23]
	v_mfma_f32_16x16x32_bf16 v[16:19], v[216:219], v[192:195], v[16:19]
	v_mfma_f32_16x16x32_bf16 v[4:7], v[208:211], v[200:203], v[4:7]
	v_mfma_f32_16x16x32_bf16 v[0:3], v[216:219], v[200:203], v[0:3]
	s_setprio 0
	s_add_u32 s71, s71, 0x8000
	s_addc_u32 s72, s72, 0
	s_add_u32 s38, s38, 0x100
	s_addc_u32 s39, s39, 0
	s_cmp_ge_u32 s73, s47
	s_mov_b32 s44, s73
	s_barrier
	s_cbranch_scc0 .LBB0_1640
	s_cmp_ge_u32 s69, 64
	s_cbranch_scc1 .Lepd_tail_hw
	s_lshl_b32 s80, s69, 21
	s_add_u32 s76, s16, s80
	s_addc_u32 s77, s17, 0
	s_add_u32 s78, s12, s80
	s_addc_u32 s79, s13, 0
	v_and_b32_e32 v132, 8, v152
	v_and_b32_e32 v146, 0xfff7, v152
	v_lshl_add_u32 v149, v132, 1, v154
	s_lshl_b32 s80, s68, 8
	s_and_b32 s80, s80, 0xff00
	v_add_u32_e32 v149, s80, v149
	v_lshlrev_b32_e32 v146, 13, v146
	v_lshl_add_u32 v146, v149, 2, v146
	v_mov_b32_e32 v147, v146
	v_add_u32_e32 v148, 0x10000, v146
	global_load_dwordx4 v[168:171], v147, s[76:77]
	global_load_dwordx4 v[172:175], v148, s[76:77]
	global_load_dwordx4 v[176:179], v147, s[76:77] offset:512
	global_load_dwordx4 v[180:183], v148, s[76:77] offset:512
	v_add_u32_e32 v147, 0x20000, v146
	v_add_u32_e32 v148, 0x30000, v146
	global_load_dwordx4 v[184:187], v147, s[76:77]
	global_load_dwordx4 v[188:191], v148, s[76:77]
	global_load_dwordx4 v[192:195], v147, s[76:77] offset:512
	global_load_dwordx4 v[196:199], v148, s[76:77] offset:512
	v_add_u32_e32 v147, 0x40000, v146
	v_add_u32_e32 v148, 0x50000, v146
	global_load_dwordx4 v[200:203], v147, s[76:77]
	global_load_dwordx4 v[204:207], v148, s[76:77]
	global_load_dwordx4 v[208:211], v147, s[76:77] offset:512
	global_load_dwordx4 v[212:215], v148, s[76:77] offset:512
	v_mov_b32_e32 v160, v120
	v_mov_b32_e32 v161, v121
	v_mov_b32_e32 v162, v122
	v_mov_b32_e32 v163, v123
	v_mov_b32_e32 v164, v112
	v_mov_b32_e32 v165, v113
	v_mov_b32_e32 v166, v114
	v_mov_b32_e32 v167, v115
	v_mov_b32_dpp v120, v124 row_ror:8 row_mask:0xf bank_mask:0x3
	v_mov_b32_dpp v121, v125 row_ror:8 row_mask:0xf bank_mask:0x3
	v_mov_b32_dpp v122, v126 row_ror:8 row_mask:0xf bank_mask:0x3
	v_mov_b32_dpp v123, v127 row_ror:8 row_mask:0xf bank_mask:0x3
	v_mov_b32_dpp v112, v116 row_ror:8 row_mask:0xf bank_mask:0x3
	v_mov_b32_dpp v113, v117 row_ror:8 row_mask:0xf bank_mask:0x3
	v_mov_b32_dpp v114, v118 row_ror:8 row_mask:0xf bank_mask:0x3
	v_mov_b32_dpp v115, v119 row_ror:8 row_mask:0xf bank_mask:0x3
	v_mov_b32_dpp v124, v160 row_ror:8 row_mask:0xf bank_mask:0xc
	v_mov_b32_dpp v125, v161 row_ror:8 row_mask:0xf bank_mask:0xc
	v_mov_b32_dpp v126, v162 row_ror:8 row_mask:0xf bank_mask:0xc
	v_mov_b32_dpp v127, v163 row_ror:8 row_mask:0xf bank_mask:0xc
	v_mov_b32_dpp v116, v164 row_ror:8 row_mask:0xf bank_mask:0xc
	v_mov_b32_dpp v117, v165 row_ror:8 row_mask:0xf bank_mask:0xc
	v_mov_b32_dpp v118, v166 row_ror:8 row_mask:0xf bank_mask:0xc
	v_mov_b32_dpp v119, v167 row_ror:8 row_mask:0xf bank_mask:0xc
	v_mov_b32_e32 v147, v146
	v_add_u32_e32 v148, 0x10000, v146
	s_waitcnt vmcnt(8)
	v_pk_add_f32 v[124:125], v[124:125], v[168:169]
	v_pk_add_f32 v[126:127], v[126:127], v[170:171]
	v_pk_add_f32 v[120:121], v[120:121], v[172:173]
	v_pk_add_f32 v[122:123], v[122:123], v[174:175]
	v_pk_add_f32 v[116:117], v[116:117], v[176:177]
	v_pk_add_f32 v[118:119], v[118:119], v[178:179]
	v_pk_add_f32 v[112:113], v[112:113], v[180:181]
	v_pk_add_f32 v[114:115], v[114:115], v[182:183]
	global_store_dwordx4 v147, v[124:127], s[78:79]
	global_store_dwordx4 v148, v[120:123], s[78:79]
	global_store_dwordx4 v147, v[116:119], s[78:79] offset:512
	global_store_dwordx4 v148, v[112:115], s[78:79] offset:512
	v_add_u32_e32 v147, 0x60000, v146
	v_add_u32_e32 v148, 0x70000, v146
	global_load_dwordx4 v[168:171], v147, s[76:77]
	global_load_dwordx4 v[172:175], v148, s[76:77]
	global_load_dwordx4 v[176:179], v147, s[76:77] offset:512
	global_load_dwordx4 v[180:183], v148, s[76:77] offset:512
	v_mov_b32_e32 v160, v104
	v_mov_b32_e32 v161, v105
	v_mov_b32_e32 v162, v106
	v_mov_b32_e32 v163, v107
	v_mov_b32_e32 v164, v96
	v_mov_b32_e32 v165, v97
	v_mov_b32_e32 v166, v98
	v_mov_b32_e32 v167, v99
	v_mov_b32_dpp v104, v108 row_ror:8 row_mask:0xf bank_mask:0x3
	v_mov_b32_dpp v105, v109 row_ror:8 row_mask:0xf bank_mask:0x3
	v_mov_b32_dpp v106, v110 row_ror:8 row_mask:0xf bank_mask:0x3
	v_mov_b32_dpp v107, v111 row_ror:8 row_mask:0xf bank_mask:0x3
	v_mov_b32_dpp v96, v100 row_ror:8 row_mask:0xf bank_mask:0x3
	v_mov_b32_dpp v97, v101 row_ror:8 row_mask:0xf bank_mask:0x3
	v_mov_b32_dpp v98, v102 row_ror:8 row_mask:0xf bank_mask:0x3
	v_mov_b32_dpp v99, v103 row_ror:8 row_mask:0xf bank_mask:0x3
	v_mov_b32_dpp v108, v160 row_ror:8 row_mask:0xf bank_mask:0xc
	v_mov_b32_dpp v109, v161 row_ror:8 row_mask:0xf bank_mask:0xc
	v_mov_b32_dpp v110, v162 row_ror:8 row_mask:0xf bank_mask:0xc
	v_mov_b32_dpp v111, v163 row_ror:8 row_mask:0xf bank_mask:0xc
	v_mov_b32_dpp v100, v164 row_ror:8 row_mask:0xf bank_mask:0xc
	v_mov_b32_dpp v101, v165 row_ror:8 row_mask:0xf bank_mask:0xc
	v_mov_b32_dpp v102, v166 row_ror:8 row_mask:0xf bank_mask:0xc
	v_mov_b32_dpp v103, v167 row_ror:8 row_mask:0xf bank_mask:0xc
	v_add_u32_e32 v147, 0x20000, v146
	v_add_u32_e32 v148, 0x30000, v146
	s_waitcnt vmcnt(12)
	v_pk_add_f32 v[108:109], v[108:109], v[184:185]
	v_pk_add_f32 v[110:111], v[110:111], v[186:187]
	v_pk_add_f32 v[104:105], v[104:105], v[188:189]
	v_pk_add_f32 v[106:107], v[106:107], v[190:191]
	v_pk_add_f32 v[100:101], v[100:101], v[192:193]
	v_pk_add_f32 v[102:103], v[102:103], v[194:195]
	v_pk_add_f32 v[96:97], v[96:97], v[196:197]
	v_pk_add_f32 v[98:99], v[98:99], v[198:199]
	global_store_dwordx4 v147, v[108:111], s[78:79]
	global_store_dwordx4 v148, v[104:107], s[78:79]
	global_store_dwordx4 v147, v[100:103], s[78:79] offset:512
	global_store_dwordx4 v148, v[96:99], s[78:79] offset:512
	v_add_u32_e32 v147, 0x100000, v146
	v_add_u32_e32 v148, 0x110000, v146
	global_load_dwordx4 v[184:187], v147, s[76:77]
	global_load_dwordx4 v[188:191], v148, s[76:77]
	global_load_dwordx4 v[192:195], v147, s[76:77] offset:512
	global_load_dwordx4 v[196:199], v148, s[76:77] offset:512
	v_mov_b32_e32 v160, v88
	v_mov_b32_e32 v161, v89
	v_mov_b32_e32 v162, v90
	v_mov_b32_e32 v163, v91
	v_mov_b32_e32 v164, v80
	v_mov_b32_e32 v165, v81
	v_mov_b32_e32 v166, v82
	v_mov_b32_e32 v167, v83
	v_mov_b32_dpp v88, v92 row_ror:8 row_mask:0xf bank_mask:0x3
	v_mov_b32_dpp v89, v93 row_ror:8 row_mask:0xf bank_mask:0x3
	v_mov_b32_dpp v90, v94 row_ror:8 row_mask:0xf bank_mask:0x3
	v_mov_b32_dpp v91, v95 row_ror:8 row_mask:0xf bank_mask:0x3
	v_mov_b32_dpp v80, v84 row_ror:8 row_mask:0xf bank_mask:0x3
	v_mov_b32_dpp v81, v85 row_ror:8 row_mask:0xf bank_mask:0x3
	v_mov_b32_dpp v82, v86 row_ror:8 row_mask:0xf bank_mask:0x3
	v_mov_b32_dpp v83, v87 row_ror:8 row_mask:0xf bank_mask:0x3
	v_mov_b32_dpp v92, v160 row_ror:8 row_mask:0xf bank_mask:0xc
	v_mov_b32_dpp v93, v161 row_ror:8 row_mask:0xf bank_mask:0xc
	v_mov_b32_dpp v94, v162 row_ror:8 row_mask:0xf bank_mask:0xc
	v_mov_b32_dpp v95, v163 row_ror:8 row_mask:0xf bank_mask:0xc
	v_mov_b32_dpp v84, v164 row_ror:8 row_mask:0xf bank_mask:0xc
	v_mov_b32_dpp v85, v165 row_ror:8 row_mask:0xf bank_mask:0xc
	v_mov_b32_dpp v86, v166 row_ror:8 row_mask:0xf bank_mask:0xc
	v_mov_b32_dpp v87, v167 row_ror:8 row_mask:0xf bank_mask:0xc
	v_add_u32_e32 v147, 0x40000, v146
	v_add_u32_e32 v148, 0x50000, v146
	s_waitcnt vmcnt(16)
	v_pk_add_f32 v[92:93], v[92:93], v[200:201]
	v_pk_add_f32 v[94:95], v[94:95], v[202:203]
	v_pk_add_f32 v[88:89], v[88:89], v[204:205]
	v_pk_add_f32 v[90:91], v[90:91], v[206:207]
	v_pk_add_f32 v[84:85], v[84:85], v[208:209]
	v_pk_add_f32 v[86:87], v[86:87], v[210:211]
	v_pk_add_f32 v[80:81], v[80:81], v[212:213]
	v_pk_add_f32 v[82:83], v[82:83], v[214:215]
	global_store_dwordx4 v147, v[92:95], s[78:79]
	global_store_dwordx4 v148, v[88:91], s[78:79]
	global_store_dwordx4 v147, v[84:87], s[78:79] offset:512
	global_store_dwordx4 v148, v[80:83], s[78:79] offset:512
	v_add_u32_e32 v147, 0x120000, v146
	v_add_u32_e32 v148, 0x130000, v146
	global_load_dwordx4 v[200:203], v147, s[76:77]
	global_load_dwordx4 v[204:207], v148, s[76:77]
	global_load_dwordx4 v[208:211], v147, s[76:77] offset:512
	global_load_dwordx4 v[212:215], v148, s[76:77] offset:512
	v_mov_b32_e32 v160, v72
	v_mov_b32_e32 v161, v73
	v_mov_b32_e32 v162, v74
	v_mov_b32_e32 v163, v75
	v_mov_b32_e32 v164, v64
	v_mov_b32_e32 v165, v65
	v_mov_b32_e32 v166, v66
	v_mov_b32_e32 v167, v67
	v_mov_b32_dpp v72, v76 row_ror:8 row_mask:0xf bank_mask:0x3
	v_mov_b32_dpp v73, v77 row_ror:8 row_mask:0xf bank_mask:0x3
	v_mov_b32_dpp v74, v78 row_ror:8 row_mask:0xf bank_mask:0x3
	v_mov_b32_dpp v75, v79 row_ror:8 row_mask:0xf bank_mask:0x3
	v_mov_b32_dpp v64, v68 row_ror:8 row_mask:0xf bank_mask:0x3
	v_mov_b32_dpp v65, v69 row_ror:8 row_mask:0xf bank_mask:0x3
	v_mov_b32_dpp v66, v70 row_ror:8 row_mask:0xf bank_mask:0x3
	v_mov_b32_dpp v67, v71 row_ror:8 row_mask:0xf bank_mask:0x3
	v_mov_b32_dpp v76, v160 row_ror:8 row_mask:0xf bank_mask:0xc
	v_mov_b32_dpp v77, v161 row_ror:8 row_mask:0xf bank_mask:0xc
	v_mov_b32_dpp v78, v162 row_ror:8 row_mask:0xf bank_mask:0xc
	v_mov_b32_dpp v79, v163 row_ror:8 row_mask:0xf bank_mask:0xc
	v_mov_b32_dpp v68, v164 row_ror:8 row_mask:0xf bank_mask:0xc
	v_mov_b32_dpp v69, v165 row_ror:8 row_mask:0xf bank_mask:0xc
	v_mov_b32_dpp v70, v166 row_ror:8 row_mask:0xf bank_mask:0xc
	v_mov_b32_dpp v71, v167 row_ror:8 row_mask:0xf bank_mask:0xc
	v_add_u32_e32 v147, 0x60000, v146
	v_add_u32_e32 v148, 0x70000, v146
	s_waitcnt vmcnt(16)
	v_pk_add_f32 v[76:77], v[76:77], v[168:169]
	v_pk_add_f32 v[78:79], v[78:79], v[170:171]
	v_pk_add_f32 v[72:73], v[72:73], v[172:173]
	v_pk_add_f32 v[74:75], v[74:75], v[174:175]
	v_pk_add_f32 v[68:69], v[68:69], v[176:177]
	v_pk_add_f32 v[70:71], v[70:71], v[178:179]
	v_pk_add_f32 v[64:65], v[64:65], v[180:181]
	v_pk_add_f32 v[66:67], v[66:67], v[182:183]
	global_store_dwordx4 v147, v[76:79], s[78:79]
	global_store_dwordx4 v148, v[72:75], s[78:79]
	global_store_dwordx4 v147, v[68:71], s[78:79] offset:512
	global_store_dwordx4 v148, v[64:67], s[78:79] offset:512
	v_add_u32_e32 v147, 0x140000, v146
	v_add_u32_e32 v148, 0x150000, v146
	global_load_dwordx4 v[168:171], v147, s[76:77]
	global_load_dwordx4 v[172:175], v148, s[76:77]
	global_load_dwordx4 v[176:179], v147, s[76:77] offset:512
	global_load_dwordx4 v[180:183], v148, s[76:77] offset:512
	v_mov_b32_e32 v160, v56
	v_mov_b32_e32 v161, v57
	v_mov_b32_e32 v162, v58
	v_mov_b32_e32 v163, v59
	v_mov_b32_e32 v164, v48
	v_mov_b32_e32 v165, v49
	v_mov_b32_e32 v166, v50
	v_mov_b32_e32 v167, v51
	v_mov_b32_dpp v56, v60 row_ror:8 row_mask:0xf bank_mask:0x3
	v_mov_b32_dpp v57, v61 row_ror:8 row_mask:0xf bank_mask:0x3
	v_mov_b32_dpp v58, v62 row_ror:8 row_mask:0xf bank_mask:0x3
	v_mov_b32_dpp v59, v63 row_ror:8 row_mask:0xf bank_mask:0x3
	v_mov_b32_dpp v48, v52 row_ror:8 row_mask:0xf bank_mask:0x3
	v_mov_b32_dpp v49, v53 row_ror:8 row_mask:0xf bank_mask:0x3
	v_mov_b32_dpp v50, v54 row_ror:8 row_mask:0xf bank_mask:0x3
	v_mov_b32_dpp v51, v55 row_ror:8 row_mask:0xf bank_mask:0x3
	v_mov_b32_dpp v60, v160 row_ror:8 row_mask:0xf bank_mask:0xc
	v_mov_b32_dpp v61, v161 row_ror:8 row_mask:0xf bank_mask:0xc
	v_mov_b32_dpp v62, v162 row_ror:8 row_mask:0xf bank_mask:0xc
	v_mov_b32_dpp v63, v163 row_ror:8 row_mask:0xf bank_mask:0xc
	v_mov_b32_dpp v52, v164 row_ror:8 row_mask:0xf bank_mask:0xc
	v_mov_b32_dpp v53, v165 row_ror:8 row_mask:0xf bank_mask:0xc
	v_mov_b32_dpp v54, v166 row_ror:8 row_mask:0xf bank_mask:0xc
	v_mov_b32_dpp v55, v167 row_ror:8 row_mask:0xf bank_mask:0xc
	v_add_u32_e32 v147, 0x100000, v146
	v_add_u32_e32 v148, 0x110000, v146
	s_waitcnt vmcnt(16)
	v_pk_add_f32 v[60:61], v[60:61], v[184:185]
	v_pk_add_f32 v[62:63], v[62:63], v[186:187]
	v_pk_add_f32 v[56:57], v[56:57], v[188:189]
	v_pk_add_f32 v[58:59], v[58:59], v[190:191]
	v_pk_add_f32 v[52:53], v[52:53], v[192:193]
	v_pk_add_f32 v[54:55], v[54:55], v[194:195]
	v_pk_add_f32 v[48:49], v[48:49], v[196:197]
	v_pk_add_f32 v[50:51], v[50:51], v[198:199]
	global_store_dwordx4 v147, v[60:63], s[78:79]
	global_store_dwordx4 v148, v[56:59], s[78:79]
	global_store_dwordx4 v147, v[52:55], s[78:79] offset:512
	global_store_dwordx4 v148, v[48:51], s[78:79] offset:512
	v_add_u32_e32 v147, 0x160000, v146
	v_add_u32_e32 v148, 0x170000, v146
	global_load_dwordx4 v[184:187], v147, s[76:77]
	global_load_dwordx4 v[188:191], v148, s[76:77]
	global_load_dwordx4 v[192:195], v147, s[76:77] offset:512
	global_load_dwordx4 v[196:199], v148, s[76:77] offset:512
	v_mov_b32_e32 v160, v40
	v_mov_b32_e32 v161, v41
	v_mov_b32_e32 v162, v42
	v_mov_b32_e32 v163, v43
	v_mov_b32_e32 v164, v32
	v_mov_b32_e32 v165, v33
	v_mov_b32_e32 v166, v34
	v_mov_b32_e32 v167, v35
	v_mov_b32_dpp v40, v44 row_ror:8 row_mask:0xf bank_mask:0x3
	v_mov_b32_dpp v41, v45 row_ror:8 row_mask:0xf bank_mask:0x3
	v_mov_b32_dpp v42, v46 row_ror:8 row_mask:0xf bank_mask:0x3
	v_mov_b32_dpp v43, v47 row_ror:8 row_mask:0xf bank_mask:0x3
	v_mov_b32_dpp v32, v36 row_ror:8 row_mask:0xf bank_mask:0x3
	v_mov_b32_dpp v33, v37 row_ror:8 row_mask:0xf bank_mask:0x3
	v_mov_b32_dpp v34, v38 row_ror:8 row_mask:0xf bank_mask:0x3
	v_mov_b32_dpp v35, v39 row_ror:8 row_mask:0xf bank_mask:0x3
	v_mov_b32_dpp v44, v160 row_ror:8 row_mask:0xf bank_mask:0xc
	v_mov_b32_dpp v45, v161 row_ror:8 row_mask:0xf bank_mask:0xc
	v_mov_b32_dpp v46, v162 row_ror:8 row_mask:0xf bank_mask:0xc
	v_mov_b32_dpp v47, v163 row_ror:8 row_mask:0xf bank_mask:0xc
	v_mov_b32_dpp v36, v164 row_ror:8 row_mask:0xf bank_mask:0xc
	v_mov_b32_dpp v37, v165 row_ror:8 row_mask:0xf bank_mask:0xc
	v_mov_b32_dpp v38, v166 row_ror:8 row_mask:0xf bank_mask:0xc
	v_mov_b32_dpp v39, v167 row_ror:8 row_mask:0xf bank_mask:0xc
	v_add_u32_e32 v147, 0x120000, v146
	v_add_u32_e32 v148, 0x130000, v146
	s_waitcnt vmcnt(16)
	v_pk_add_f32 v[44:45], v[44:45], v[200:201]
	v_pk_add_f32 v[46:47], v[46:47], v[202:203]
	v_pk_add_f32 v[40:41], v[40:41], v[204:205]
	v_pk_add_f32 v[42:43], v[42:43], v[206:207]
	v_pk_add_f32 v[36:37], v[36:37], v[208:209]
	v_pk_add_f32 v[38:39], v[38:39], v[210:211]
	v_pk_add_f32 v[32:33], v[32:33], v[212:213]
	v_pk_add_f32 v[34:35], v[34:35], v[214:215]
	global_store_dwordx4 v147, v[44:47], s[78:79]
	global_store_dwordx4 v148, v[40:43], s[78:79]
	global_store_dwordx4 v147, v[36:39], s[78:79] offset:512
	global_store_dwordx4 v148, v[32:35], s[78:79] offset:512
	v_mov_b32_e32 v160, v24
	v_mov_b32_e32 v161, v25
	v_mov_b32_e32 v162, v26
	v_mov_b32_e32 v163, v27
	v_mov_b32_e32 v164, v16
	v_mov_b32_e32 v165, v17
	v_mov_b32_e32 v166, v18
	v_mov_b32_e32 v167, v19
	v_mov_b32_dpp v24, v28 row_ror:8 row_mask:0xf bank_mask:0x3
	v_mov_b32_dpp v25, v29 row_ror:8 row_mask:0xf bank_mask:0x3
	v_mov_b32_dpp v26, v30 row_ror:8 row_mask:0xf bank_mask:0x3
	v_mov_b32_dpp v27, v31 row_ror:8 row_mask:0xf bank_mask:0x3
	v_mov_b32_dpp v16, v20 row_ror:8 row_mask:0xf bank_mask:0x3
	v_mov_b32_dpp v17, v21 row_ror:8 row_mask:0xf bank_mask:0x3
	v_mov_b32_dpp v18, v22 row_ror:8 row_mask:0xf bank_mask:0x3
	v_mov_b32_dpp v19, v23 row_ror:8 row_mask:0xf bank_mask:0x3
	v_mov_b32_dpp v28, v160 row_ror:8 row_mask:0xf bank_mask:0xc
	v_mov_b32_dpp v29, v161 row_ror:8 row_mask:0xf bank_mask:0xc
	v_mov_b32_dpp v30, v162 row_ror:8 row_mask:0xf bank_mask:0xc
	v_mov_b32_dpp v31, v163 row_ror:8 row_mask:0xf bank_mask:0xc
	v_mov_b32_dpp v20, v164 row_ror:8 row_mask:0xf bank_mask:0xc
	v_mov_b32_dpp v21, v165 row_ror:8 row_mask:0xf bank_mask:0xc
	v_mov_b32_dpp v22, v166 row_ror:8 row_mask:0xf bank_mask:0xc
	v_mov_b32_dpp v23, v167 row_ror:8 row_mask:0xf bank_mask:0xc
	v_add_u32_e32 v147, 0x140000, v146
	v_add_u32_e32 v148, 0x150000, v146
	s_waitcnt vmcnt(12)
	v_pk_add_f32 v[28:29], v[28:29], v[168:169]
	v_pk_add_f32 v[30:31], v[30:31], v[170:171]
	v_pk_add_f32 v[24:25], v[24:25], v[172:173]
	v_pk_add_f32 v[26:27], v[26:27], v[174:175]
	v_pk_add_f32 v[20:21], v[20:21], v[176:177]
	v_pk_add_f32 v[22:23], v[22:23], v[178:179]
	v_pk_add_f32 v[16:17], v[16:17], v[180:181]
	v_pk_add_f32 v[18:19], v[18:19], v[182:183]
	global_store_dwordx4 v147, v[28:31], s[78:79]
	global_store_dwordx4 v148, v[24:27], s[78:79]
	global_store_dwordx4 v147, v[20:23], s[78:79] offset:512
	global_store_dwordx4 v148, v[16:19], s[78:79] offset:512
	v_mov_b32_e32 v160, v8
	v_mov_b32_e32 v161, v9
	v_mov_b32_e32 v162, v10
	v_mov_b32_e32 v163, v11
	v_mov_b32_e32 v164, v0
	v_mov_b32_e32 v165, v1
	v_mov_b32_e32 v166, v2
	v_mov_b32_e32 v167, v3
	v_mov_b32_dpp v8, v12 row_ror:8 row_mask:0xf bank_mask:0x3
	v_mov_b32_dpp v9, v13 row_ror:8 row_mask:0xf bank_mask:0x3
	v_mov_b32_dpp v10, v14 row_ror:8 row_mask:0xf bank_mask:0x3
	v_mov_b32_dpp v11, v15 row_ror:8 row_mask:0xf bank_mask:0x3
	v_mov_b32_dpp v0, v4 row_ror:8 row_mask:0xf bank_mask:0x3
	v_mov_b32_dpp v1, v5 row_ror:8 row_mask:0xf bank_mask:0x3
	v_mov_b32_dpp v2, v6 row_ror:8 row_mask:0xf bank_mask:0x3
	v_mov_b32_dpp v3, v7 row_ror:8 row_mask:0xf bank_mask:0x3
	v_mov_b32_dpp v12, v160 row_ror:8 row_mask:0xf bank_mask:0xc
	v_mov_b32_dpp v13, v161 row_ror:8 row_mask:0xf bank_mask:0xc
	v_mov_b32_dpp v14, v162 row_ror:8 row_mask:0xf bank_mask:0xc
	v_mov_b32_dpp v15, v163 row_ror:8 row_mask:0xf bank_mask:0xc
	v_mov_b32_dpp v4, v164 row_ror:8 row_mask:0xf bank_mask:0xc
	v_mov_b32_dpp v5, v165 row_ror:8 row_mask:0xf bank_mask:0xc
	v_mov_b32_dpp v6, v166 row_ror:8 row_mask:0xf bank_mask:0xc
	v_mov_b32_dpp v7, v167 row_ror:8 row_mask:0xf bank_mask:0xc
	v_add_u32_e32 v147, 0x160000, v146
	v_add_u32_e32 v148, 0x170000, v146
	s_waitcnt vmcnt(8)
	v_pk_add_f32 v[12:13], v[12:13], v[184:185]
	v_pk_add_f32 v[14:15], v[14:15], v[186:187]
	v_pk_add_f32 v[8:9], v[8:9], v[188:189]
	v_pk_add_f32 v[10:11], v[10:11], v[190:191]
	v_pk_add_f32 v[4:5], v[4:5], v[192:193]
	v_pk_add_f32 v[6:7], v[6:7], v[194:195]
	v_pk_add_f32 v[0:1], v[0:1], v[196:197]
	v_pk_add_f32 v[2:3], v[2:3], v[198:199]
	global_store_dwordx4 v147, v[12:15], s[78:79]
	global_store_dwordx4 v148, v[8:11], s[78:79]
	global_store_dwordx4 v147, v[4:7], s[78:79] offset:512
	global_store_dwordx4 v148, v[0:3], s[78:79] offset:512
	s_branch .LBB0_1625
.Lepd_orig:
.Lepd_tail_hw:
	v_and_b32_e32 v132, 0x1c0, v156
	v_lshlrev_b32_e32 v132, 5, v132
	v_add_u32_e32 v132, 0x20000, v132
	v_and_b32_e32 v146, 15, v152
	v_and_b32_e32 v147, 12, v154
	v_lshlrev_b32_e32 v146, 7, v146
	v_lshl_add_u32 v146, v147, 2, v146
	v_add_u32_e32 v146, v132, v146
	v_and_b32_e32 v147, 63, v156
	v_lshl_add_u32 v147, v147, 2, v132
	v_and_b32_e32 v148, 0x40, v152
	v_bfe_u32 v149, v156, 5, 1
	v_add_u32_e32 v148, v148, v149
	v_lshlrev_b32_e32 v148, 13, v148
	v_and_b32_e32 v149, 0x60, v154
	v_and_b32_e32 v150, 31, v156
	v_add_u32_e32 v149, v149, v150
	s_lshl_b32 s80, s68, 8
	s_and_b32 s80, s80, 0xff00
	v_add_u32_e32 v149, s80, v149
	v_lshl_add_u32 v148, v149, 2, v148
	ds_write_b128 v146, v[124:127]
	ds_write_b128 v146, v[120:123] offset:64
	ds_read_b32 v160, v147
	ds_read_b32 v161, v147 offset:256
	ds_read_b32 v162, v147 offset:512
	ds_read_b32 v163, v147 offset:768
	ds_read_b32 v164, v147 offset:1024
	ds_read_b32 v165, v147 offset:1280
	ds_read_b32 v166, v147 offset:1536
	ds_read_b32 v167, v147 offset:1792
	s_add_u32 s76, s24, 0x0
	s_addc_u32 s77, s25, 0
	s_waitcnt lgkmcnt(7)
	global_atomic_add_f32 v148, v160, s[76:77]
	s_add_u32 s76, s24, 0x4000
	s_addc_u32 s77, s25, 0
	s_waitcnt lgkmcnt(6)
	global_atomic_add_f32 v148, v161, s[76:77]
	s_add_u32 s76, s24, 0x8000
	s_addc_u32 s77, s25, 0
	s_waitcnt lgkmcnt(5)
	global_atomic_add_f32 v148, v162, s[76:77]
	s_add_u32 s76, s24, 0xc000
	s_addc_u32 s77, s25, 0
	s_waitcnt lgkmcnt(4)
	global_atomic_add_f32 v148, v163, s[76:77]
	s_add_u32 s76, s24, 0x10000
	s_addc_u32 s77, s25, 0
	s_waitcnt lgkmcnt(3)
	global_atomic_add_f32 v148, v164, s[76:77]
	s_add_u32 s76, s24, 0x14000
	s_addc_u32 s77, s25, 0
	s_waitcnt lgkmcnt(2)
	global_atomic_add_f32 v148, v165, s[76:77]
	s_add_u32 s76, s24, 0x18000
	s_addc_u32 s77, s25, 0
	s_waitcnt lgkmcnt(1)
	global_atomic_add_f32 v148, v166, s[76:77]
	s_add_u32 s76, s24, 0x1c000
	s_addc_u32 s77, s25, 0
	s_waitcnt lgkmcnt(0)
	global_atomic_add_f32 v148, v167, s[76:77]
	ds_write_b128 v146, v[116:119]
	ds_write_b128 v146, v[112:115] offset:64
	ds_read_b32 v160, v147
	ds_read_b32 v161, v147 offset:256
	ds_read_b32 v162, v147 offset:512
	ds_read_b32 v163, v147 offset:768
	ds_read_b32 v164, v147 offset:1024
	ds_read_b32 v165, v147 offset:1280
	ds_read_b32 v166, v147 offset:1536
	ds_read_b32 v167, v147 offset:1792
	s_add_u32 s76, s24, 0x0
	s_addc_u32 s77, s25, 0
	s_waitcnt lgkmcnt(7)
	global_atomic_add_f32 v148, v160, s[76:77] offset:512
	s_add_u32 s76, s24, 0x4000
	s_addc_u32 s77, s25, 0
	s_waitcnt lgkmcnt(6)
	global_atomic_add_f32 v148, v161, s[76:77] offset:512
	s_add_u32 s76, s24, 0x8000
	s_addc_u32 s77, s25, 0
	s_waitcnt lgkmcnt(5)
	global_atomic_add_f32 v148, v162, s[76:77] offset:512
	s_add_u32 s76, s24, 0xc000
	s_addc_u32 s77, s25, 0
	s_waitcnt lgkmcnt(4)
	global_atomic_add_f32 v148, v163, s[76:77] offset:512
	s_add_u32 s76, s24, 0x10000
	s_addc_u32 s77, s25, 0
	s_waitcnt lgkmcnt(3)
	global_atomic_add_f32 v148, v164, s[76:77] offset:512
	s_add_u32 s76, s24, 0x14000
	s_addc_u32 s77, s25, 0
	s_waitcnt lgkmcnt(2)
	global_atomic_add_f32 v148, v165, s[76:77] offset:512
	s_add_u32 s76, s24, 0x18000
	s_addc_u32 s77, s25, 0
	s_waitcnt lgkmcnt(1)
	global_atomic_add_f32 v148, v166, s[76:77] offset:512
	s_add_u32 s76, s24, 0x1c000
	s_addc_u32 s77, s25, 0
	s_waitcnt lgkmcnt(0)
	global_atomic_add_f32 v148, v167, s[76:77] offset:512
	ds_write_b128 v146, v[108:111]
	ds_write_b128 v146, v[104:107] offset:64
	ds_read_b32 v160, v147
	ds_read_b32 v161, v147 offset:256
	ds_read_b32 v162, v147 offset:512
	ds_read_b32 v163, v147 offset:768
	ds_read_b32 v164, v147 offset:1024
	ds_read_b32 v165, v147 offset:1280
	ds_read_b32 v166, v147 offset:1536
	ds_read_b32 v167, v147 offset:1792
	s_add_u32 s76, s24, 0x20000
	s_addc_u32 s77, s25, 0
	s_waitcnt lgkmcnt(7)
	global_atomic_add_f32 v148, v160, s[76:77]
	s_add_u32 s76, s24, 0x24000
	s_addc_u32 s77, s25, 0
	s_waitcnt lgkmcnt(6)
	global_atomic_add_f32 v148, v161, s[76:77]
	s_add_u32 s76, s24, 0x28000
	s_addc_u32 s77, s25, 0
	s_waitcnt lgkmcnt(5)
	global_atomic_add_f32 v148, v162, s[76:77]
	s_add_u32 s76, s24, 0x2c000
	s_addc_u32 s77, s25, 0
	s_waitcnt lgkmcnt(4)
	global_atomic_add_f32 v148, v163, s[76:77]
	s_add_u32 s76, s24, 0x30000
	s_addc_u32 s77, s25, 0
	s_waitcnt lgkmcnt(3)
	global_atomic_add_f32 v148, v164, s[76:77]
	s_add_u32 s76, s24, 0x34000
	s_addc_u32 s77, s25, 0
	s_waitcnt lgkmcnt(2)
	global_atomic_add_f32 v148, v165, s[76:77]
	s_add_u32 s76, s24, 0x38000
	s_addc_u32 s77, s25, 0
	s_waitcnt lgkmcnt(1)
	global_atomic_add_f32 v148, v166, s[76:77]
	s_add_u32 s76, s24, 0x3c000
	s_addc_u32 s77, s25, 0
	s_waitcnt lgkmcnt(0)
	global_atomic_add_f32 v148, v167, s[76:77]
	ds_write_b128 v146, v[100:103]
	ds_write_b128 v146, v[96:99] offset:64
	ds_read_b32 v160, v147
	ds_read_b32 v161, v147 offset:256
	ds_read_b32 v162, v147 offset:512
	ds_read_b32 v163, v147 offset:768
	ds_read_b32 v164, v147 offset:1024
	ds_read_b32 v165, v147 offset:1280
	ds_read_b32 v166, v147 offset:1536
	ds_read_b32 v167, v147 offset:1792
	s_add_u32 s76, s24, 0x20000
	s_addc_u32 s77, s25, 0
	s_waitcnt lgkmcnt(7)
	global_atomic_add_f32 v148, v160, s[76:77] offset:512
	s_add_u32 s76, s24, 0x24000
	s_addc_u32 s77, s25, 0
	s_waitcnt lgkmcnt(6)
	global_atomic_add_f32 v148, v161, s[76:77] offset:512
	s_add_u32 s76, s24, 0x28000
	s_addc_u32 s77, s25, 0
	s_waitcnt lgkmcnt(5)
	global_atomic_add_f32 v148, v162, s[76:77] offset:512
	s_add_u32 s76, s24, 0x2c000
	s_addc_u32 s77, s25, 0
	s_waitcnt lgkmcnt(4)
	global_atomic_add_f32 v148, v163, s[76:77] offset:512
	s_add_u32 s76, s24, 0x30000
	s_addc_u32 s77, s25, 0
	s_waitcnt lgkmcnt(3)
	global_atomic_add_f32 v148, v164, s[76:77] offset:512
	s_add_u32 s76, s24, 0x34000
	s_addc_u32 s77, s25, 0
	s_waitcnt lgkmcnt(2)
	global_atomic_add_f32 v148, v165, s[76:77] offset:512
	s_add_u32 s76, s24, 0x38000
	s_addc_u32 s77, s25, 0
	s_waitcnt lgkmcnt(1)
	global_atomic_add_f32 v148, v166, s[76:77] offset:512
	s_add_u32 s76, s24, 0x3c000
	s_addc_u32 s77, s25, 0
	s_waitcnt lgkmcnt(0)
	global_atomic_add_f32 v148, v167, s[76:77] offset:512
	ds_write_b128 v146, v[92:95]
	ds_write_b128 v146, v[88:91] offset:64
	ds_read_b32 v160, v147
	ds_read_b32 v161, v147 offset:256
	ds_read_b32 v162, v147 offset:512
	ds_read_b32 v163, v147 offset:768
	ds_read_b32 v164, v147 offset:1024
	ds_read_b32 v165, v147 offset:1280
	ds_read_b32 v166, v147 offset:1536
	ds_read_b32 v167, v147 offset:1792
	s_add_u32 s76, s24, 0x40000
	s_addc_u32 s77, s25, 0
	s_waitcnt lgkmcnt(7)
	global_atomic_add_f32 v148, v160, s[76:77]
	s_add_u32 s76, s24, 0x44000
	s_addc_u32 s77, s25, 0
	s_waitcnt lgkmcnt(6)
	global_atomic_add_f32 v148, v161, s[76:77]
	s_add_u32 s76, s24, 0x48000
	s_addc_u32 s77, s25, 0
	s_waitcnt lgkmcnt(5)
	global_atomic_add_f32 v148, v162, s[76:77]
	s_add_u32 s76, s24, 0x4c000
	s_addc_u32 s77, s25, 0
	s_waitcnt lgkmcnt(4)
	global_atomic_add_f32 v148, v163, s[76:77]
	s_add_u32 s76, s24, 0x50000
	s_addc_u32 s77, s25, 0
	s_waitcnt lgkmcnt(3)
	global_atomic_add_f32 v148, v164, s[76:77]
	s_add_u32 s76, s24, 0x54000
	s_addc_u32 s77, s25, 0
	s_waitcnt lgkmcnt(2)
	global_atomic_add_f32 v148, v165, s[76:77]
	s_add_u32 s76, s24, 0x58000
	s_addc_u32 s77, s25, 0
	s_waitcnt lgkmcnt(1)
	global_atomic_add_f32 v148, v166, s[76:77]
	s_add_u32 s76, s24, 0x5c000
	s_addc_u32 s77, s25, 0
	s_waitcnt lgkmcnt(0)
	global_atomic_add_f32 v148, v167, s[76:77]
	ds_write_b128 v146, v[84:87]
	ds_write_b128 v146, v[80:83] offset:64
	ds_read_b32 v160, v147
	ds_read_b32 v161, v147 offset:256
	ds_read_b32 v162, v147 offset:512
	ds_read_b32 v163, v147 offset:768
	ds_read_b32 v164, v147 offset:1024
	ds_read_b32 v165, v147 offset:1280
	ds_read_b32 v166, v147 offset:1536
	ds_read_b32 v167, v147 offset:1792
	s_add_u32 s76, s24, 0x40000
	s_addc_u32 s77, s25, 0
	s_waitcnt lgkmcnt(7)
	global_atomic_add_f32 v148, v160, s[76:77] offset:512
	s_add_u32 s76, s24, 0x44000
	s_addc_u32 s77, s25, 0
	s_waitcnt lgkmcnt(6)
	global_atomic_add_f32 v148, v161, s[76:77] offset:512
	s_add_u32 s76, s24, 0x48000
	s_addc_u32 s77, s25, 0
	s_waitcnt lgkmcnt(5)
	global_atomic_add_f32 v148, v162, s[76:77] offset:512
	s_add_u32 s76, s24, 0x4c000
	s_addc_u32 s77, s25, 0
	s_waitcnt lgkmcnt(4)
	global_atomic_add_f32 v148, v163, s[76:77] offset:512
	s_add_u32 s76, s24, 0x50000
	s_addc_u32 s77, s25, 0
	s_waitcnt lgkmcnt(3)
	global_atomic_add_f32 v148, v164, s[76:77] offset:512
	s_add_u32 s76, s24, 0x54000
	s_addc_u32 s77, s25, 0
	s_waitcnt lgkmcnt(2)
	global_atomic_add_f32 v148, v165, s[76:77] offset:512
	s_add_u32 s76, s24, 0x58000
	s_addc_u32 s77, s25, 0
	s_waitcnt lgkmcnt(1)
	global_atomic_add_f32 v148, v166, s[76:77] offset:512
	s_add_u32 s76, s24, 0x5c000
	s_addc_u32 s77, s25, 0
	s_waitcnt lgkmcnt(0)
	global_atomic_add_f32 v148, v167, s[76:77] offset:512
	ds_write_b128 v146, v[76:79]
	ds_write_b128 v146, v[72:75] offset:64
	ds_read_b32 v160, v147
	ds_read_b32 v161, v147 offset:256
	ds_read_b32 v162, v147 offset:512
	ds_read_b32 v163, v147 offset:768
	ds_read_b32 v164, v147 offset:1024
	ds_read_b32 v165, v147 offset:1280
	ds_read_b32 v166, v147 offset:1536
	ds_read_b32 v167, v147 offset:1792
	s_add_u32 s76, s24, 0x60000
	s_addc_u32 s77, s25, 0
	s_waitcnt lgkmcnt(7)
	global_atomic_add_f32 v148, v160, s[76:77]
	s_add_u32 s76, s24, 0x64000
	s_addc_u32 s77, s25, 0
	s_waitcnt lgkmcnt(6)
	global_atomic_add_f32 v148, v161, s[76:77]
	s_add_u32 s76, s24, 0x68000
	s_addc_u32 s77, s25, 0
	s_waitcnt lgkmcnt(5)
	global_atomic_add_f32 v148, v162, s[76:77]
	s_add_u32 s76, s24, 0x6c000
	s_addc_u32 s77, s25, 0
	s_waitcnt lgkmcnt(4)
	global_atomic_add_f32 v148, v163, s[76:77]
	s_add_u32 s76, s24, 0x70000
	s_addc_u32 s77, s25, 0
	s_waitcnt lgkmcnt(3)
	global_atomic_add_f32 v148, v164, s[76:77]
	s_add_u32 s76, s24, 0x74000
	s_addc_u32 s77, s25, 0
	s_waitcnt lgkmcnt(2)
	global_atomic_add_f32 v148, v165, s[76:77]
	s_add_u32 s76, s24, 0x78000
	s_addc_u32 s77, s25, 0
	s_waitcnt lgkmcnt(1)
	global_atomic_add_f32 v148, v166, s[76:77]
	s_add_u32 s76, s24, 0x7c000
	s_addc_u32 s77, s25, 0
	s_waitcnt lgkmcnt(0)
	global_atomic_add_f32 v148, v167, s[76:77]
	ds_write_b128 v146, v[68:71]
	ds_write_b128 v146, v[64:67] offset:64
	ds_read_b32 v160, v147
	ds_read_b32 v161, v147 offset:256
	ds_read_b32 v162, v147 offset:512
	ds_read_b32 v163, v147 offset:768
	ds_read_b32 v164, v147 offset:1024
	ds_read_b32 v165, v147 offset:1280
	ds_read_b32 v166, v147 offset:1536
	ds_read_b32 v167, v147 offset:1792
	s_add_u32 s76, s24, 0x60000
	s_addc_u32 s77, s25, 0
	s_waitcnt lgkmcnt(7)
	global_atomic_add_f32 v148, v160, s[76:77] offset:512
	s_add_u32 s76, s24, 0x64000
	s_addc_u32 s77, s25, 0
	s_waitcnt lgkmcnt(6)
	global_atomic_add_f32 v148, v161, s[76:77] offset:512
	s_add_u32 s76, s24, 0x68000
	s_addc_u32 s77, s25, 0
	s_waitcnt lgkmcnt(5)
	global_atomic_add_f32 v148, v162, s[76:77] offset:512
	s_add_u32 s76, s24, 0x6c000
	s_addc_u32 s77, s25, 0
	s_waitcnt lgkmcnt(4)
	global_atomic_add_f32 v148, v163, s[76:77] offset:512
	s_add_u32 s76, s24, 0x70000
	s_addc_u32 s77, s25, 0
	s_waitcnt lgkmcnt(3)
	global_atomic_add_f32 v148, v164, s[76:77] offset:512
	s_add_u32 s76, s24, 0x74000
	s_addc_u32 s77, s25, 0
	s_waitcnt lgkmcnt(2)
	global_atomic_add_f32 v148, v165, s[76:77] offset:512
	s_add_u32 s76, s24, 0x78000
	s_addc_u32 s77, s25, 0
	s_waitcnt lgkmcnt(1)
	global_atomic_add_f32 v148, v166, s[76:77] offset:512
	s_add_u32 s76, s24, 0x7c000
	s_addc_u32 s77, s25, 0
	s_waitcnt lgkmcnt(0)
	global_atomic_add_f32 v148, v167, s[76:77] offset:512
	s_branch .LBB0_1625
